# tile order in three panel groups (6,6,5) for gemm1/gemmG/gemm4
# speedup vs baseline: 1.0409x; 1.0105x over previous
.LBB0_154:
	s_cmp_ge_u32 s3, 180
	s_cbranch_scc1 .Lto_g1_0
	s_sub_u32 s99, s3, 0
	s_mul_hi_u32 s98, s99, 0xaaaaaaab
	s_lshr_b32 s98, s98, 2
	s_mul_i32 s100, s98, 6
	s_sub_u32 s99, s99, s100
	s_branch .Lto_j_0
.Lto_g1_0:
	s_cmp_ge_u32 s3, 360
	s_cbranch_scc1 .Lto_g2_0
	s_sub_u32 s99, s3, 180
	s_mul_hi_u32 s98, s99, 0xaaaaaaab
	s_lshr_b32 s98, s98, 2
	s_mul_i32 s100, s98, 6
	s_sub_u32 s99, s99, s100
	s_add_u32 s99, s99, 6
	s_branch .Lto_j_0
.Lto_g2_0:
	s_sub_u32 s99, s3, 360
	s_mul_hi_u32 s98, s99, 0xcccccccd
	s_lshr_b32 s98, s98, 2
	s_mul_i32 s100, s98, 5
	s_sub_u32 s99, s99, s100
	s_add_u32 s99, s99, 12

.LBB0_608:
	s_cmp_ge_u32 s3, 192
	s_cbranch_scc1 .Lto_g1_1
	s_sub_u32 s99, s3, 0
	s_mul_hi_u32 s98, s99, 0xaaaaaaab
	s_lshr_b32 s98, s98, 2
	s_mul_i32 s100, s98, 6
	s_sub_u32 s99, s99, s100
	s_branch .Lto_j_1
.Lto_g1_1:
	s_cmp_ge_u32 s3, 384
	s_cbranch_scc1 .Lto_g2_1
	s_sub_u32 s99, s3, 192
	s_mul_hi_u32 s98, s99, 0xaaaaaaab
	s_lshr_b32 s98, s98, 2
	s_mul_i32 s100, s98, 6
	s_sub_u32 s99, s99, s100
	s_add_u32 s99, s99, 6
	s_branch .Lto_j_1
.Lto_g2_1:
	s_sub_u32 s99, s3, 384
	s_mul_hi_u32 s98, s99, 0xcccccccd
	s_lshr_b32 s98, s98, 2
	s_mul_i32 s100, s98, 5
	s_sub_u32 s99, s99, s100
	s_add_u32 s99, s99, 12

.LBB0_882:
	s_cmp_ge_u32 s3, 264
	s_cbranch_scc1 .Lto_g1_2
	s_sub_u32 s99, s3, 0
	s_mul_hi_u32 s98, s99, 0xaaaaaaab
	s_lshr_b32 s98, s98, 2
	s_mul_i32 s100, s98, 6
	s_sub_u32 s99, s99, s100
	s_branch .Lto_j_2
.Lto_g1_2:
	s_cmp_ge_u32 s3, 528
	s_cbranch_scc1 .Lto_g2_2
	s_sub_u32 s99, s3, 264
	s_mul_hi_u32 s98, s99, 0xaaaaaaab
	s_lshr_b32 s98, s98, 2
	s_mul_i32 s100, s98, 6
	s_sub_u32 s99, s99, s100
	s_add_u32 s99, s99, 6
	s_branch .Lto_j_2
.Lto_g2_2:
	s_sub_u32 s99, s3, 528
	s_mul_hi_u32 s98, s99, 0xcccccccd
	s_lshr_b32 s98, s98, 2
	s_mul_i32 s100, s98, 5
	s_sub_u32 s99, s99, s100
	s_add_u32 s99, s99, 12
